# v32 + phaseX row sum of squares: 64-lane reduction by DPP inside rows and v_readlane across rows instead of a 6-hop ds_bpermute butterfly (12 LDS round trips per trip)
# speedup vs baseline: 1.0029x; 1.0029x over previous
; __device__ __forceinline__ unsigned cvt_pk_bf16(float lo, float hi) { const f32x2 v = {lo, hi}; return __builtin_bit_cast(unsigned, __builtin_convertvector(v, bf16x2_t)); }
; __device__ __forceinline__ void phaseX(int l, int s) {
;     ...
;     for (int mb = gw; mb < MS; mb += 4096) {
;         f32x4 v[2][4], pv[2]; size_t rg[2];
; #pragma unroll
;         for (int u = 0; u < 2; ++u) { const int m = mb + 2048 * u; rg[u] = (size_t)((m >> 11) * 4096 + s * 2048 + (m & 2047)); const f32x4* xr = (const f32x4*)(xin + rg[u] * 1024);
; #pragma unroll
;             for (int i = 0; i < 4; ++i) v[u][i] = xr[lane + 64 * i];
;             pv[u] = *(const f32x4*)(pin + rg[u] * 256 + lane * 4); }
; #pragma unroll
;         for (int u = 0; u < 2; ++u) { const int m = mb + 2048 * u; float sum = 0.f;
; #pragma unroll
;             for (int i = 0; i < 4; ++i) { const f32x4 x = v[u][i]; sum += x[0] * x[0] + x[1] * x[1] + x[2] * x[2] + x[3] * x[3]; }
;             sum = wsum(sum);
;             const float rs = rsqrtf(sum * (1.0f / 1024.0f) + 1e-6f);
; #pragma unroll
;             for (int i = 0; i < 4; ++i) { const f32x4 x = v[u][i] * rs;
;                 u32x2 w; w.x = cvt_pk_bf16(x[0], x[1]); w.y = cvt_pk_bf16(x[2], x[3]); *(u32x2*)(B.xb + (size_t)m * 1024 + (lane + 64 * i) * 4) = w; }
;             if (lane == 0) { B.ss1[m] = 0.f; B.ss2[m] = 0.f; }
.LBB0_154:
	v_and_b32_e32 v0, 0x7ff, v40
	v_or_b32_e32 v0, s22, v0
	s_movk_i32 s20, 0xf000
	v_and_or_b32 v0, v47, s20, v0
	v_ashrrev_i32_e32 v1, 31, v0
	v_lshlrev_b64 v[2:3], 12, v[0:1]
	v_lshl_add_u64 v[2:3], v[26:27], 0, v[2:3]
	global_load_dwordx4 v[48:51], v[2:3], off
	global_load_dwordx4 v[52:55], v[2:3], off offset:1024
	global_load_dwordx4 v[56:59], v[2:3], off offset:2048
	global_load_dwordx4 v[60:63], v[2:3], off offset:3072
	v_add_u32_e32 v2, 0x1000, v0
	v_lshlrev_b64 v[0:1], 10, v[0:1]
	v_ashrrev_i32_e32 v3, 31, v2
	v_lshl_add_u64 v[0:1], v[24:25], 0, v[0:1]
	v_lshlrev_b64 v[4:5], 12, v[2:3]
	v_lshlrev_b64 v[2:3], 10, v[2:3]
	global_load_dwordx4 v[20:23], v[0:1], off
	v_lshl_add_u64 v[0:1], v[26:27], 0, v[4:5]
	v_lshl_add_u64 v[2:3], v[24:25], 0, v[2:3]
	global_load_dwordx4 v[16:19], v[0:1], off
	global_load_dwordx4 v[12:15], v[0:1], off offset:1024
	global_load_dwordx4 v[8:11], v[0:1], off offset:2048
	global_load_dwordx4 v[4:7], v[0:1], off offset:3072
	s_nop 0
	global_load_dwordx4 v[0:3], v[2:3], off
	s_waitcnt vmcnt(9)
	v_mov_b32_e32 v66, v49
	s_waitcnt vmcnt(8)
	v_mov_b32_e32 v67, v53
	v_mov_b32_e32 v64, v48
	v_mov_b32_e32 v65, v52
	s_waitcnt vmcnt(7)
	v_mov_b32_e32 v74, v57
	s_waitcnt vmcnt(6)
	v_mov_b32_e32 v75, v61
	v_pk_mul_f32 v[66:67], v[66:67], v[66:67]
	v_mov_b32_e32 v68, v50
	v_mov_b32_e32 v69, v54
	v_mov_b32_e32 v72, v56
	v_mov_b32_e32 v73, v60
	v_pk_mul_f32 v[74:75], v[74:75], v[74:75]
	v_pk_fma_f32 v[64:65], v[64:65], v[64:65], v[66:67]
	v_mov_b32_e32 v70, v51
	v_mov_b32_e32 v71, v55
	v_mov_b32_e32 v76, v58
	v_mov_b32_e32 v77, v62
	v_pk_fma_f32 v[66:67], v[72:73], v[72:73], v[74:75]
	v_pk_fma_f32 v[64:65], v[68:69], v[68:69], v[64:65]
	v_mov_b32_e32 v78, v59
	v_mov_b32_e32 v79, v63
	v_pk_fma_f32 v[66:67], v[76:77], v[76:77], v[66:67]
	v_pk_fma_f32 v[64:65], v[70:71], v[70:71], v[64:65]
	v_pk_fma_f32 v[66:67], v[78:79], v[78:79], v[66:67]
	v_add_f32_e32 v64, v64, v65
	v_add_f32_e32 v64, v64, v66
	v_add_f32_e32 v64, v64, v67
	s_nop 1
	v_add_f32_dpp v64, v64, v64 quad_perm:[1,0,3,2] row_mask:0xf bank_mask:0xf bound_ctrl:1
	s_nop 1
	v_add_f32_dpp v64, v64, v64 quad_perm:[2,3,0,1] row_mask:0xf bank_mask:0xf bound_ctrl:1
	s_nop 1
	v_add_f32_dpp v64, v64, v64 row_half_mirror row_mask:0xf bank_mask:0xf bound_ctrl:1
	s_nop 1
	v_add_f32_dpp v64, v64, v64 row_mirror row_mask:0xf bank_mask:0xf bound_ctrl:1
	s_nop 1
	v_readlane_b32 s21, v64, 0
	s_nop 1
	v_mov_b32_e32 v65, s21
	v_readlane_b32 s21, v64, 16
	s_nop 1
	v_add_f32_e32 v65, s21, v65
	v_readlane_b32 s21, v64, 32
	s_nop 1
	v_add_f32_e32 v65, s21, v65
	v_readlane_b32 s21, v64, 48
	s_nop 1
	v_add_f32_e32 v64, s21, v65
	v_fmamk_f32 v64, v64, 0x3a800000, v178
	v_mul_f32_e32 v65, 0x4b800000, v64
	v_cmp_gt_f32_e32 vcc, s33, v64
	s_nop 1
	v_cndmask_b32_e32 v64, v64, v65, vcc
	v_rsq_f32_e32 v66, v64
	v_lshl_add_u64 v[64:65], s[16:17], 0, v[38:39]
	v_mul_f32_e32 v67, 0x45800000, v66
	v_cndmask_b32_e32 v66, v66, v67, vcc
	v_pk_mul_f32 v[50:51], v[50:51], v[66:67] op_sel_hi:[1,0]
	v_pk_mul_f32 v[48:49], v[48:49], v[66:67] op_sel_hi:[1,0]
	v_pk_mul_f32 v[54:55], v[54:55], v[66:67] op_sel_hi:[1,0]
	v_pk_mul_f32 v[52:53], v[52:53], v[66:67] op_sel_hi:[1,0]
	v_pk_mul_f32 v[58:59], v[58:59], v[66:67] op_sel_hi:[1,0]
	v_pk_mul_f32 v[56:57], v[56:57], v[66:67] op_sel_hi:[1,0]
	v_pk_mul_f32 v[62:63], v[62:63], v[66:67] op_sel_hi:[1,0]
	v_pk_mul_f32 v[60:61], v[60:61], v[66:67] op_sel_hi:[1,0]
	v_cvt_pk_bf16_f32 v48, v48, v49
	v_cvt_pk_bf16_f32 v49, v50, v51
	v_cvt_pk_bf16_f32 v50, v52, v53
	v_cvt_pk_bf16_f32 v51, v54, v55
	v_cvt_pk_bf16_f32 v52, v56, v57
	v_cvt_pk_bf16_f32 v53, v58, v59
	v_cvt_pk_bf16_f32 v54, v60, v61
	v_cvt_pk_bf16_f32 v55, v62, v63
	global_store_dwordx2 v[64:65], v[48:49], off offset:-1024
	global_store_dwordx2 v[64:65], v[50:51], off offset:-512
	global_store_dwordx2 v[64:65], v[52:53], off
	global_store_dwordx2 v[64:65], v[54:55], off offset:512
	s_and_saveexec_b64 s[20:21], s[38:39]
	s_cbranch_execz .LBB0_156
	v_lshl_add_u64 v[48:49], s[16:17], 0, v[34:35]
	v_add_co_u32_e32 v50, vcc, 0x7e10000, v48
	s_nop 1
	v_addc_co_u32_e32 v51, vcc, 0, v49, vcc
	v_add_co_u32_e32 v48, vcc, 0x7e20000, v48
	global_store_dword v[50:51], v177, off
	s_nop 0
	v_addc_co_u32_e32 v49, vcc, 0, v49, vcc
	global_store_dword v[48:49], v177, off
; __device__ __forceinline__ unsigned cvt_pk_bf16(float lo, float hi) { const f32x2 v = {lo, hi}; return __builtin_bit_cast(unsigned, __builtin_convertvector(v, bf16x2_t)); }
; __device__ __forceinline__ void phaseX(int l, int s) {
;     ...
;         for (int u = 0; u < 2; ++u) { const int m = mb + 2048 * u; float sum = 0.f;
; #pragma unroll
;             for (int i = 0; i < 4; ++i) { const f32x4 x = v[u][i]; sum += x[0] * x[0] + x[1] * x[1] + x[2] * x[2] + x[3] * x[3]; }
;             sum = wsum(sum);
;             const float rs = rsqrtf(sum * (1.0f / 1024.0f) + 1e-6f);
; #pragma unroll
;             for (int i = 0; i < 4; ++i) { const f32x4 x = v[u][i] * rs;
;                 u32x2 w; w.x = cvt_pk_bf16(x[0], x[1]); w.y = cvt_pk_bf16(x[2], x[3]); *(u32x2*)(B.xb + (size_t)m * 1024 + (lane + 64 * i) * 4) = w; }
;             if (lane == 0) { B.ss1[m] = 0.f; B.ss2[m] = 0.f; }
;             u32x2 w; w.x = cvt_pk_bf16(pv[u][0], pv[u][1]); w.y = cvt_pk_bf16(pv[u][2], pv[u][3]); *(u32x2*)(B.pb + (size_t)m * 256 + lane * 4) = w; }
.LBB0_156:
	s_or_b64 exec, exec, s[20:21]
	s_waitcnt vmcnt(8)
	v_mov_b32_e32 v50, v17
	s_waitcnt vmcnt(7)
	v_mov_b32_e32 v51, v13
	v_mov_b32_e32 v48, v16
	v_mov_b32_e32 v49, v12
	v_pk_mul_f32 v[50:51], v[50:51], v[50:51]
	s_waitcnt vmcnt(6)
	v_mov_b32_e32 v52, v9
	v_pk_fma_f32 v[48:49], v[48:49], v[48:49], v[50:51]
	v_mov_b32_e32 v50, v18
	v_mov_b32_e32 v51, v14
	v_pk_fma_f32 v[48:49], v[50:51], v[50:51], v[48:49]
	v_mov_b32_e32 v50, v19
	v_mov_b32_e32 v51, v15
	s_waitcnt vmcnt(5)
	v_mov_b32_e32 v53, v5
	v_pk_fma_f32 v[48:49], v[50:51], v[50:51], v[48:49]
	v_mov_b32_e32 v50, v8
	v_mov_b32_e32 v51, v4
	v_pk_mul_f32 v[52:53], v[52:53], v[52:53]
	v_add_f32_e32 v48, v48, v49
	v_pk_fma_f32 v[50:51], v[50:51], v[50:51], v[52:53]
	v_mov_b32_e32 v52, v10
	v_mov_b32_e32 v53, v6
	v_pk_fma_f32 v[50:51], v[52:53], v[52:53], v[50:51]
	v_mov_b32_e32 v52, v11
	v_mov_b32_e32 v53, v7
	v_pk_fma_f32 v[50:51], v[52:53], v[52:53], v[50:51]
	v_cvt_pk_bf16_f32 v20, v20, v21
	v_add_f32_e32 v48, v48, v50
	v_add_f32_e32 v48, v48, v51
	v_cvt_pk_bf16_f32 v21, v22, v23
	s_mov_b32 s20, 0x5600000
	s_nop 1
	v_add_f32_dpp v48, v48, v48 quad_perm:[1,0,3,2] row_mask:0xf bank_mask:0xf bound_ctrl:1
	s_nop 1
	v_add_f32_dpp v48, v48, v48 quad_perm:[2,3,0,1] row_mask:0xf bank_mask:0xf bound_ctrl:1
	s_nop 1
	v_add_f32_dpp v48, v48, v48 row_half_mirror row_mask:0xf bank_mask:0xf bound_ctrl:1
	s_nop 1
	v_add_f32_dpp v48, v48, v48 row_mirror row_mask:0xf bank_mask:0xf bound_ctrl:1
	s_nop 1
	v_readlane_b32 s21, v48, 0
	s_nop 1
	v_mov_b32_e32 v49, s21
	v_readlane_b32 s21, v48, 16
	s_nop 1
	v_add_f32_e32 v49, s21, v49
	v_readlane_b32 s21, v48, 32
	s_nop 1
	v_add_f32_e32 v49, s21, v49
	v_readlane_b32 s21, v48, 48
	s_nop 1
	v_add_f32_e32 v22, s21, v49
	v_fmamk_f32 v22, v22, 0x3a800000, v178
	v_mul_f32_e32 v23, 0x4b800000, v22
	v_cmp_gt_f32_e32 vcc, s33, v22
	v_lshl_add_u64 v[48:49], s[16:17], 0, v[32:33]
	s_nop 0
	v_cndmask_b32_e32 v22, v22, v23, vcc
	v_rsq_f32_e32 v50, v22
	v_lshl_add_u64 v[22:23], s[16:17], 0, v[36:37]
	global_store_dwordx2 v[22:23], v[20:21], off
	v_mul_f32_e32 v20, 0x45800000, v50
	v_cndmask_b32_e32 v20, v50, v20, vcc
	v_pk_mul_f32 v[18:19], v[18:19], v[20:21] op_sel_hi:[1,0]
	v_pk_mul_f32 v[16:17], v[16:17], v[20:21] op_sel_hi:[1,0]
	v_pk_mul_f32 v[14:15], v[14:15], v[20:21] op_sel_hi:[1,0]
	v_cvt_pk_bf16_f32 v16, v16, v17
	v_cvt_pk_bf16_f32 v17, v18, v19
	v_add_co_u32_e32 v18, vcc, s20, v48
	v_pk_mul_f32 v[12:13], v[12:13], v[20:21] op_sel_hi:[1,0]
	v_pk_mul_f32 v[10:11], v[10:11], v[20:21] op_sel_hi:[1,0]
	v_pk_mul_f32 v[8:9], v[8:9], v[20:21] op_sel_hi:[1,0]
	v_pk_mul_f32 v[6:7], v[6:7], v[20:21] op_sel_hi:[1,0]
	v_pk_mul_f32 v[4:5], v[4:5], v[20:21] op_sel_hi:[1,0]
	v_addc_co_u32_e32 v19, vcc, 0, v49, vcc
	v_cvt_pk_bf16_f32 v12, v12, v13
	v_cvt_pk_bf16_f32 v13, v14, v15
	v_cvt_pk_bf16_f32 v8, v8, v9
	v_cvt_pk_bf16_f32 v9, v10, v11
	v_cvt_pk_bf16_f32 v4, v4, v5
	v_cvt_pk_bf16_f32 v5, v6, v7
	global_store_dwordx2 v[18:19], v[16:17], off
	global_store_dwordx2 v[18:19], v[12:13], off offset:512
	global_store_dwordx2 v[18:19], v[8:9], off offset:1024
	global_store_dwordx2 v[18:19], v[4:5], off offset:1536
	s_and_saveexec_b64 s[20:21], s[38:39]
	s_cbranch_execz .LBB0_153
	v_lshl_add_u64 v[4:5], s[16:17], 0, v[28:29]
	v_add_co_u32_e32 v6, vcc, 0x7e10000, v4
	s_nop 1
	v_addc_co_u32_e32 v7, vcc, 0, v5, vcc
	v_add_co_u32_e32 v4, vcc, 0x7e20000, v4
	global_store_dword v[6:7], v177, off
	s_nop 0
	v_addc_co_u32_e32 v5, vcc, 0, v5, vcc
	global_store_dword v[4:5], v177, off
	s_branch .LBB0_153
